# indexer prologue: second key tile's loads issued with the prologue loads instead of after its vmcnt(0); pre-loop wait vmcnt(4)
# speedup vs baseline: 1.0100x; 1.0031x over previous
; __device__ __forceinline__ void indexer_phase(const bf16_t* PJ, float* rk, unsigned short* SEL, LAS unsigned char* lds) {
;     ...
;         const int b = gl >> 9, jj = gl & 511, t0 = (jj < 256 ? jj : 767 - jj) * 8;
;         const size_t rowbase = (size_t)b * SEQ;
;         const int t = t0 + wid;
;         unsigned short* selrow = SEL + (rowbase + t) * 256;
;         if (t0 + 7 < 256) {
; #pragma unroll
;             for (int i = 0; i < 4; ++i) { const int s = lane + 64 * i; selrow[s] = (unsigned short)(s <= t ? s : 0); }
;             continue;
;         }
;         {
;             const int g = r32 >> 3, hp = (r32 >> 2) & 1, ii = r32 & 3, tq = 2 * hp + (g >> 1), head = 4 * (g & 1) + ii;
;             bf16x8 af[2][4]; float wq[2][2][8];
; #pragma unroll
;             for (int rt = 0; rt < 2; ++rt) {
;                 const bf16_t* qp = PJ + (rowbase + t0 + 4 * rt + tq) * PROJ_LD + PJ_QI + head * 64 + hi * 8;
; #pragma unroll
;                 for (int kk = 0; kk < 4; ++kk) af[rt][kk] = *(const bf16x8*)(qp + kk * 16);
; #pragma unroll
;                 for (int qq = 0; qq < 2; ++qq) { const u32x4 w = *(const u32x4*)(PJ + (rowbase + t0 + 4 * rt + 2 * hi + qq) * PROJ_LD + PJ_WI);
;                     const float sc = 0.35355339059327373f;
;                     wq[rt][qq][0] = bflo(w.x) * sc; wq[rt][qq][1] = bfhi(w.x) * sc; wq[rt][qq][2] = bflo(w.y) * sc; wq[rt][qq][3] = bfhi(w.y) * sc;
;                     wq[rt][qq][4] = bflo(w.z) * sc; wq[rt][qq][5] = bfhi(w.z) * sc; wq[rt][qq][6] = bflo(w.w) * sc; wq[rt][qq][7] = bfhi(w.w) * sc; }
;             }
;             float rmax[2][2], rmin[2][2];
; #pragma unroll
;             for (int rt = 0; rt < 2; ++rt)
; #pragma unroll
;                 for (int qq = 0; qq < 2; ++qq) { rmax[rt][qq] = -INFINITY; rmin[rt][qq] = INFINITY; }
;             const int nkt = (t0 + 8 + 31) >> 5;
;             const bf16_t* kbase = PJ + (rowbase + r32) * PROJ_LD + PJ_KI + hi * 8;
;             bf16x8 bcur[4], bnxt[4];
;             int kt = wid;
; #pragma unroll
;             for (int kk = 0; kk < 4; ++kk) bcur[kk] = *(const bf16x8*)(kbase + (size_t)(32 * kt) * PROJ_LD + kk * 16);
.LBB0_864:
	s_and_b32 s0, s2, 0x1ff
	s_ashr_i32 s24, s2, 9
	s_sub_i32 s1, 0x2ff, s0
	s_cmpk_lt_u32 s0, 0x100
	s_cselect_b32 s0, s0, s1
	s_lshl_b32 s1, s0, 3
	s_ashr_i32 s25, s24, 31
	s_add_i32 s77, s1, s33
	s_lshl_b64 s[26:27], s[24:25], 12
	s_ashr_i32 s3, s77, 31
	s_add_u32 s24, s26, s77
	s_addc_u32 s25, s27, s3
	s_lshl_b64 s[24:25], s[24:25], 9
	s_add_u32 s60, s4, s24
	s_addc_u32 s61, s5, s25
	s_cmp_gt_u32 s0, 31
	s_mov_b64 s[24:25], -1
	s_cbranch_scc0 .LBB0_1027
	s_add_i32 s0, s1, 39
	s_lshr_b32 s0, s0, 5
	s_cmp_ge_i32 s33, s0
	s_cbranch_scc1 .LBB0_873
	v_readlane_b32 s24, v255, 13
	s_add_u32 s3, s26, s1
	v_readlane_b32 s25, v255, 14
	v_or_b32_e32 v0, s3, v112
	s_addc_u32 s6, s27, 0
	v_mov_b64_e32 v[16:17], s[24:25]
	v_mad_u64_u32 v[0:1], s[24:25], v0, s7, v[16:17]
	v_mad_i32_i24 v1, s6, v177, v1
	v_lshl_add_u64 v[0:1], v[0:1], 0, v[114:115]
	v_mov_b32_e32 v123, v115
	v_lshl_add_u64 v[18:19], v[0:1], 0, v[122:123]
	v_or_b32_e32 v0, s3, v116
	v_add_co_u32_e32 v20, vcc, s44, v18
	v_mad_u64_u32 v[0:1], s[24:25], v0, s7, v[16:17]
	v_mad_i32_i24 v1, s6, v177, v1
	s_mov_b64 s[24:25], vcc
	v_add_co_u32_e32 v0, vcc, s44, v0
	v_or_b32_e32 v4, s3, v120
	s_nop 0
	v_addc_co_u32_e32 v1, vcc, 0, v1, vcc
	v_mad_u64_u32 v[4:5], s[28:29], v4, s7, v[16:17]
	s_or_b32 s3, s3, 4
	v_mad_i32_i24 v5, s6, v177, v5
	v_add_co_u32_e32 v4, vcc, s44, v4
	v_or_b32_e32 v8, s3, v116
	s_nop 0
	v_addc_co_u32_e32 v5, vcc, 0, v5, vcc
	v_mad_u64_u32 v[8:9], s[28:29], v8, s7, v[16:17]
	v_mad_i32_i24 v9, s6, v177, v9
	v_add_co_u32_e32 v8, vcc, s44, v8
	v_or_b32_e32 v12, s3, v120
	s_nop 0
	v_addc_co_u32_e32 v9, vcc, 0, v9, vcc
	s_mov_b64 s[30:31], 0x1100
	s_waitcnt lgkmcnt(0)
	v_mad_u64_u32 v[12:13], s[28:29], v12, s7, v[16:17]
	v_lshl_add_u64 v[22:23], v[18:19], 0, s[30:31]
	v_mad_i32_i24 v13, s6, v177, v13
	v_add_co_u32_e32 v12, vcc, s44, v12
	v_or_b32_e32 v18, s3, v112
	global_load_dwordx4 v[0:3], v[0:1], off offset:1408
	v_addc_co_u32_e32 v13, vcc, 0, v13, vcc
	v_addc_co_u32_e64 v21, vcc, 0, v19, s[24:25]
	v_mad_u64_u32 v[18:19], s[24:25], v18, s7, v[16:17]
	v_mad_i32_i24 v19, s6, v177, v19
	global_load_dwordx4 v[4:7], v[4:5], off offset:1408
	v_lshl_add_u64 v[18:19], v[18:19], 0, v[114:115]
	v_lshl_add_u64 v[18:19], v[18:19], 0, v[122:123]
	global_load_dwordx4 v[8:11], v[8:9], off offset:1408
	v_or_b32_e32 v190, s1, v116
	global_load_dwordx4 v[12:15], v[12:13], off offset:1408
	s_nop 0
	global_load_dwordx4 v[64:67], v[22:23], off offset:32
	global_load_dwordx4 v[68:71], v[22:23], off offset:64
	global_load_dwordx4 v[72:75], v[20:21], off offset:256
	global_load_dwordx4 v[76:79], v[22:23], off offset:96
	v_lshl_add_u64 v[20:21], v[18:19], 0, s[30:31]
	v_add_co_u32_e32 v22, vcc, s44, v18
	v_or_b32_e32 v18, s26, v110
	v_mad_u64_u32 v[16:17], s[24:25], v18, s7, v[16:17]
	v_mad_i32_i24 v17, s27, v177, v17
	v_lshl_add_u64 v[16:17], v[16:17], 0, v[122:123]
	s_mov_b64 s[24:25], 0x1500
	v_lshl_add_u64 v[124:125], v[16:17], 0, s[24:25]
	v_lshl_add_u64 v[216:217], v[218:219], 0, v[124:125]
	v_readlane_b32 s24, v255, 21
	v_readlane_b32 s25, v255, 22
	v_addc_co_u32_e32 v23, vcc, 0, v19, vcc
	s_nop 0
	v_lshl_add_u64 v[16:17], v[124:125], 0, s[24:25]
	global_load_dwordx4 v[80:83], v[20:21], off offset:32
	global_load_dwordx4 v[84:87], v[20:21], off offset:64
	global_load_dwordx4 v[96:99], v[16:17], off offset:96
	global_load_dwordx4 v[100:103], v[16:17], off offset:64
	global_load_dwordx4 v[104:107], v[16:17], off offset:32
	s_nop 0
	global_load_dwordx4 v[244:247], v[16:17], off
	s_nop 0
	global_load_dwordx4 v[88:91], v[22:23], off offset:256
	global_load_dwordx4 v[92:95], v[20:21], off offset:96
	v_readlane_b32 s32, v255, 20
	s_add_i32 s32, s32, 0x100
	v_mad_i64_i32 v[248:249], s[28:29], s32, v177, v[216:217]
	s_add_i32 s32, s32, 16
	v_mad_i64_i32 v[250:251], s[28:29], s32, v177, v[216:217]
	global_load_dwordx4 v[52:55], v[248:249], off
	global_load_dwordx4 v[56:59], v[250:251], off
	global_load_dwordx4 v[60:63], v[248:249], off offset:64
	global_load_dwordx4 v[48:51], v[250:251], off offset:64
	v_or_b32_e32 v191, 1, v190
	v_or_b32_e32 v192, 4, v190
	v_or_b32_e32 v193, 5, v190
	v_mov_b32_e32 v189, 0xff800000
	v_mov_b32_e32 v188, 0x7f800000
	v_mov_b32_e32 v196, v171
	v_readlane_b32 s6, v255, 20
	v_mov_b32_e32 v186, 0x7f800000
	v_mov_b32_e32 v184, 0x7f800000
	v_mov_b32_e32 v123, 0x7f800000
	v_mov_b32_e32 v187, 0xff800000
	v_mov_b32_e32 v185, 0xff800000
	v_mov_b32_e32 v183, 0xff800000
	s_mov_b32 s1, s33
	s_waitcnt vmcnt(19)
	v_and_b32_e32 v20, 0xffff0000, v0
	v_lshlrev_b32_e32 v21, 16, v0
	v_and_b32_e32 v0, 0xffff0000, v1
	v_lshlrev_b32_e32 v1, 16, v1
	v_pk_mul_f32 v[128:129], v[0:1], s[58:59] op_sel_hi:[1,0]
	v_and_b32_e32 v0, 0xffff0000, v3
	v_lshlrev_b32_e32 v1, 16, v3
	v_pk_mul_f32 v[132:133], v[0:1], s[58:59] op_sel_hi:[1,0]
	s_waitcnt vmcnt(18)
	v_and_b32_e32 v0, 0xffff0000, v4
	v_lshlrev_b32_e32 v1, 16, v4
	v_pk_mul_f32 v[134:135], v[0:1], s[58:59] op_sel_hi:[1,0]
	v_and_b32_e32 v0, 0xffff0000, v5
	v_lshlrev_b32_e32 v1, 16, v5
	v_pk_mul_f32 v[136:137], v[0:1], s[58:59] op_sel_hi:[1,0]
	v_and_b32_e32 v0, 0xffff0000, v6
	v_lshlrev_b32_e32 v1, 16, v6
	v_pk_mul_f32 v[138:139], v[0:1], s[58:59] op_sel_hi:[1,0]
	v_and_b32_e32 v0, 0xffff0000, v7
	v_lshlrev_b32_e32 v1, 16, v7
	v_pk_mul_f32 v[140:141], v[0:1], s[58:59] op_sel_hi:[1,0]
	s_waitcnt vmcnt(17)
	v_and_b32_e32 v0, 0xffff0000, v8
	v_lshlrev_b32_e32 v1, 16, v8
	v_pk_mul_f32 v[142:143], v[0:1], s[58:59] op_sel_hi:[1,0]
	v_and_b32_e32 v0, 0xffff0000, v9
	v_lshlrev_b32_e32 v1, 16, v9
	v_pk_mul_f32 v[144:145], v[0:1], s[58:59] op_sel_hi:[1,0]
	v_and_b32_e32 v0, 0xffff0000, v10
	v_lshlrev_b32_e32 v1, 16, v10
	v_pk_mul_f32 v[146:147], v[0:1], s[58:59] op_sel_hi:[1,0]
	v_and_b32_e32 v0, 0xffff0000, v11
	v_lshlrev_b32_e32 v1, 16, v11
	v_pk_mul_f32 v[148:149], v[0:1], s[58:59] op_sel_hi:[1,0]
	s_waitcnt vmcnt(16)
	v_and_b32_e32 v0, 0xffff0000, v12
	v_lshlrev_b32_e32 v1, 16, v12
	v_pk_mul_f32 v[150:151], v[0:1], s[58:59] op_sel_hi:[1,0]
	v_and_b32_e32 v0, 0xffff0000, v13
	v_lshlrev_b32_e32 v1, 16, v13
	v_pk_mul_f32 v[152:153], v[0:1], s[58:59] op_sel_hi:[1,0]
	v_and_b32_e32 v0, 0xffff0000, v14
	v_lshlrev_b32_e32 v1, 16, v14
	v_and_b32_e32 v22, 0xffff0000, v2
	v_lshlrev_b32_e32 v23, 16, v2
	v_pk_mul_f32 v[154:155], v[0:1], s[58:59] op_sel_hi:[1,0]
	v_and_b32_e32 v0, 0xffff0000, v15
	v_lshlrev_b32_e32 v1, 16, v15
	v_pk_mul_f32 v[126:127], v[20:21], s[58:59] op_sel_hi:[1,0]
	v_pk_mul_f32 v[130:131], v[22:23], s[58:59] op_sel_hi:[1,0]
	v_pk_mul_f32 v[156:157], v[0:1], s[58:59] op_sel_hi:[1,0]
	s_waitcnt vmcnt(4)

; #define LAS __attribute__((address_space(3)))
; __device__ __forceinline__ void indexer_phase(const bf16_t* PJ, float* rk, unsigned short* SEL, LAS unsigned char* lds) {
;     ...
;                 const int key = 32 * kt + r32;
; #pragma unroll
;                 for (int rt = 0; rt < 2; ++rt) {
;                     f32x16 acc = f32x16{};
; #pragma unroll
;                     for (int kk = 0; kk < 4; ++kk) acc = __builtin_amdgcn_mfma_f32_32x32x16_bf16(af[rt][kk], bcur[kk], acc, 0, 0, 0);
; #pragma unroll
;                     for (int qq = 0; qq < 2; ++qq) { float s = 0.f;
; #pragma unroll
;                         for (int e = 0; e < 8; ++e) s += wq[rt][qq][e] * fmaxf(acc[8 * qq + e], 0.f);
;                         ((LAS float*)lds)[(4 * rt + 2 * hi + qq) * 4096 + key] = s;
;                         const bool ok = key <= t0 + 4 * rt + 2 * hi + qq;
;                         rmax[rt][qq] = fmaxf(rmax[rt][qq], ok ? s : -INFINITY); rmin[rt][qq] = fminf(rmin[rt][qq], ok ? s : INFINITY); }
.Lidx_last:
	s_waitcnt vmcnt(0) lgkmcnt(0)
	v_mfma_f32_32x32x16_bf16 v[0:15], v[72:75], v[244:247], 0
	v_add_u32_e32 v197, s6, v110
	v_mfma_f32_32x32x16_bf16 v[0:15], v[64:67], v[104:107], v[0:15]
	v_mfma_f32_32x32x16_bf16 v[0:15], v[68:71], v[100:103], v[0:15]
	v_mfma_f32_32x32x16_bf16 v[0:15], v[76:79], v[96:99], v[0:15]
	v_mfma_f32_32x32x16_bf16 v[16:31], v[88:91], v[244:247], 0
	v_mfma_f32_32x32x16_bf16 v[16:31], v[80:83], v[104:107], v[16:31]
	v_mfma_f32_32x32x16_bf16 v[16:31], v[84:87], v[100:103], v[16:31]
	v_mfma_f32_32x32x16_bf16 v[16:31], v[92:95], v[96:99], v[16:31]
	s_nop 7
	v_max_f32_e32 v0, 0, v0
	v_max_f32_e32 v1, 0, v1
	v_max_f32_e32 v2, 0, v2
	v_max_f32_e32 v3, 0, v3
	v_max_f32_e32 v4, 0, v4
	v_max_f32_e32 v5, 0, v5
	v_max_f32_e32 v6, 0, v6
	v_max_f32_e32 v7, 0, v7
	v_pk_mul_f32 v[0:1], v[126:127], v[0:1] op_sel:[1,0] op_sel_hi:[0,1]
	v_pk_fma_f32 v[0:1], v[128:129], v[2:3], v[0:1] op_sel:[1,0,0] op_sel_hi:[0,1,1]
	v_pk_fma_f32 v[0:1], v[130:131], v[4:5], v[0:1] op_sel:[1,0,0] op_sel_hi:[0,1,1]
	v_pk_fma_f32 v[0:1], v[132:133], v[6:7], v[0:1] op_sel:[1,0,0] op_sel_hi:[0,1,1]
	v_add_f32_e32 v0, v1, v0
	v_max_f32_e32 v8, 0, v8
	v_max_f32_e32 v9, 0, v9
	v_max_f32_e32 v10, 0, v10
	v_max_f32_e32 v11, 0, v11
	v_max_f32_e32 v12, 0, v12
	v_max_f32_e32 v13, 0, v13
	v_max_f32_e32 v14, 0, v14
	v_max_f32_e32 v15, 0, v15
	v_pk_mul_f32 v[8:9], v[134:135], v[8:9] op_sel:[1,0] op_sel_hi:[0,1]
	v_pk_fma_f32 v[8:9], v[136:137], v[10:11], v[8:9] op_sel:[1,0,0] op_sel_hi:[0,1,1]
	v_pk_fma_f32 v[8:9], v[138:139], v[12:13], v[8:9] op_sel:[1,0,0] op_sel_hi:[0,1,1]
	v_pk_fma_f32 v[8:9], v[140:141], v[14:15], v[8:9] op_sel:[1,0,0] op_sel_hi:[0,1,1]
	v_cmp_gt_i32_e32 vcc, v197, v190
	s_nop 1
	v_cndmask_b32_e32 v1, v0, v178, vcc
	v_cndmask_b32_e32 v2, v0, v179, vcc
	v_max_f32_e32 v189, v189, v1
	v_min_f32_e32 v188, v188, v2
	v_add_f32_e32 v8, v9, v8
	v_cmp_gt_i32_e32 vcc, v197, v191
	ds_write2st64_b32 v196, v0, v8 offset1:64
	v_max_f32_e32 v16, 0, v16
	v_max_f32_e32 v17, 0, v17
	v_max_f32_e32 v18, 0, v18
	v_cndmask_b32_e32 v1, v8, v178, vcc
	v_cndmask_b32_e32 v2, v8, v179, vcc
	v_max_f32_e32 v187, v187, v1
	v_min_f32_e32 v186, v186, v2
	v_max_f32_e32 v19, 0, v19
	v_max_f32_e32 v20, 0, v20
	v_max_f32_e32 v21, 0, v21
	v_max_f32_e32 v22, 0, v22
	v_max_f32_e32 v23, 0, v23
	v_pk_mul_f32 v[16:17], v[142:143], v[16:17] op_sel:[1,0] op_sel_hi:[0,1]
	v_pk_fma_f32 v[16:17], v[144:145], v[18:19], v[16:17] op_sel:[1,0,0] op_sel_hi:[0,1,1]
	v_pk_fma_f32 v[16:17], v[146:147], v[20:21], v[16:17] op_sel:[1,0,0] op_sel_hi:[0,1,1]
	v_pk_fma_f32 v[16:17], v[148:149], v[22:23], v[16:17] op_sel:[1,0,0] op_sel_hi:[0,1,1]
	v_add_f32_e32 v16, v17, v16
	v_max_f32_e32 v24, 0, v24
	v_max_f32_e32 v25, 0, v25
	v_max_f32_e32 v26, 0, v26
	v_max_f32_e32 v27, 0, v27
	v_max_f32_e32 v28, 0, v28
	v_max_f32_e32 v29, 0, v29
	v_max_f32_e32 v30, 0, v30
	v_max_f32_e32 v31, 0, v31
	v_pk_mul_f32 v[24:25], v[150:151], v[24:25] op_sel:[1,0] op_sel_hi:[0,1]
	v_pk_fma_f32 v[24:25], v[152:153], v[26:27], v[24:25] op_sel:[1,0,0] op_sel_hi:[0,1,1]
	v_pk_fma_f32 v[24:25], v[154:155], v[28:29], v[24:25] op_sel:[1,0,0] op_sel_hi:[0,1,1]
	v_pk_fma_f32 v[24:25], v[156:157], v[30:31], v[24:25] op_sel:[1,0,0] op_sel_hi:[0,1,1]
	v_cmp_gt_i32_e32 vcc, v197, v192
	v_add_u32_e32 v3, 0x10000, v196
	s_nop 1
	ds_write_b32 v3, v16
	v_cndmask_b32_e32 v1, v16, v178, vcc
	v_cndmask_b32_e32 v2, v16, v179, vcc
	v_max_f32_e32 v185, v185, v1
	v_min_f32_e32 v184, v184, v2
	v_add_f32_e32 v24, v25, v24
	v_cmp_gt_i32_e32 vcc, v197, v193
	v_add_u32_e32 v3, 0x14000, v196
	v_add_u32_e32 v196, 0x400, v196
	s_nop 0
	ds_write_b32 v3, v24
	v_cndmask_b32_e32 v1, v24, v178, vcc
	v_cndmask_b32_e32 v2, v24, v179, vcc
	v_max_f32_e32 v183, v183, v1
	v_min_f32_e32 v123, v123, v2
	s_branch .LBB0_874
